# attention: second-half K/V global loads issued inside the P.V tr-read wait window (after the 8 tr reads, before lgkmcnt(0))
# baseline (speedup 1.0000x reference)
; #define SBAR() __builtin_amdgcn_sched_barrier(0)
; __device__ __forceinline__ void partialSM(f32x16& p0, f32x16& p1, float& m_reg, float& mn, float& alpha) {
;   constexpr float C = SCALE * 1.4426950408889634f;
;   float pmax = p0[0]; for (int r = 1; r < 16; ++r) pmax = fmaxf(pmax, p0[r]); for (int r = 0; r < 16; ++r) pmax = fmaxf(pmax, p1[r]);
;   { auto rr = __builtin_amdgcn_permlane32_swap(__float_as_uint(pmax), __float_as_uint(pmax), false, false);
;     pmax = fmaxf(__uint_as_float(rr[0]), __uint_as_float(rr[1])); }
;   if (__builtin_expect(__all(pmax - m_reg <= THR / SCALE), 1)) { mn = m_reg; alpha = 1.f; }
;   else { mn = fmaxf(m_reg, pmax); alpha = __builtin_amdgcn_exp2f((m_reg - mn) * C); m_reg = mn; }
; template <int OFF> __device__ __forceinline__ s16x4 tr_read(int vb) {
;   s16x4 r; asm volatile("ds_read_b64_tr_b16 %0, %1 offset:%2" : "=&v"(r) : "v"(vb), "i"(OFF) : "memory"); return r;
; }
; template <int D0> __device__ __forceinline__ void pv_one(f32x16& od, int vb, bf16x8 pa0, bf16x8 pa1, bf16x8 pa2, bf16x8 pa3) {
;   const s16x4 l0 = tr_read<v_rd_off(D0, 0, 0)>(vb), h0 = tr_read<v_rd_off(D0, 0, 1)>(vb), l1 = tr_read<v_rd_off(D0, 1, 0)>(vb), h1 = tr_read<v_rd_off(D0, 1, 1)>(vb);
;   const s16x4 l2 = tr_read<v_rd_off(D0, 2, 0)>(vb), h2 = tr_read<v_rd_off(D0, 2, 1)>(vb), l3 = tr_read<v_rd_off(D0, 3, 0)>(vb), h3 = tr_read<v_rd_off(D0, 3, 1)>(vb);
;   asm volatile("s_waitcnt lgkmcnt(0)" ::: "memory"); SBAR();
;     ...
;   od = __builtin_amdgcn_mfma_f32_32x32x16_bf16(pa0, PK(l0, h0), od, 0, 0, 0);
;   od = __builtin_amdgcn_mfma_f32_32x32x16_bf16(pa1, PK(l1, h1), od, 0, 0, 0);
;   od = __builtin_amdgcn_mfma_f32_32x32x16_bf16(pa2, PK(l2, h2), od, 0, 0, 0);
;   od = __builtin_amdgcn_mfma_f32_32x32x16_bf16(pa3, PK(l3, h3), od, 0, 0, 0);
;     ...
; }
; __device__ __forceinline__ void pv_d0(f32x16* o, int vb, bf16x8 pa0, bf16x8 pa1, bf16x8 pa2, bf16x8 pa3) {
;   pv_one<0>(o[0], vb, pa0, pa1, pa2, pa3); pv_one<1>(o[1], vb, pa0, pa1, pa2, pa3); pv_one<2>(o[2], vb, pa0, pa1, pa2, pa3); pv_one<3>(o[3], vb, pa0, pa1, pa2, pa3);
.LBB0_581:
	ds_read_b64_tr_b16 v[210:211], v184 offset:16384
	ds_read_b64_tr_b16 v[212:213], v184 offset:18432
	ds_read_b64_tr_b16 v[214:215], v184 offset:20480
	ds_read_b64_tr_b16 v[216:217], v184 offset:22528
	ds_read_b64_tr_b16 v[224:225], v184 offset:24576
	ds_read_b64_tr_b16 v[226:227], v184 offset:26624
	ds_read_b64_tr_b16 v[228:229], v184 offset:28672
	ds_read_b64_tr_b16 v[230:231], v184 offset:30720
	s_cbranch_vccnz .Lattn_skip_loads
	global_load_dwordx4 v[128:131], v176, s[52:53]
	global_load_dwordx4 v[132:135], v176, s[52:53] offset:-512
	s_add_u32 s52, s52, 0x18000
	s_addc_u32 s53, s53, 0
	global_load_dwordx4 v[136:139], v176, s[52:53]
	global_load_dwordx4 v[140:143], v176, s[52:53] offset:-512
	s_add_u32 s52, s52, 0x18000
	s_addc_u32 s53, s53, 0
.Lattn_after_loads:
	s_waitcnt lgkmcnt(0)
	v_mfma_f32_32x32x16_bf16 v[0:15], v[160:163], v[210:213], v[0:15]
	ds_read_b64_tr_b16 v[210:211], v184 offset:16896
	ds_read_b64_tr_b16 v[212:213], v184 offset:18944
	v_mfma_f32_32x32x16_bf16 v[0:15], v[164:167], v[214:217], v[0:15]
	ds_read_b64_tr_b16 v[214:215], v184 offset:20992
	ds_read_b64_tr_b16 v[216:217], v184 offset:23040
	v_mfma_f32_32x32x16_bf16 v[0:15], v[168:171], v[224:227], v[0:15]
	ds_read_b64_tr_b16 v[224:225], v184 offset:25088
	ds_read_b64_tr_b16 v[226:227], v184 offset:27136
	v_mfma_f32_32x32x16_bf16 v[0:15], v[172:175], v[228:231], v[0:15]
	ds_read_b64_tr_b16 v[228:229], v184 offset:29184
	ds_read_b64_tr_b16 v[230:231], v184 offset:31232
	s_waitcnt lgkmcnt(0)
	v_mfma_f32_32x32x16_bf16 v[48:63], v[160:163], v[210:213], v[48:63]
	ds_read_b64_tr_b16 v[210:211], v184 offset:17408
	ds_read_b64_tr_b16 v[212:213], v184 offset:19456
	v_mfma_f32_32x32x16_bf16 v[48:63], v[164:167], v[214:217], v[48:63]
	ds_read_b64_tr_b16 v[214:215], v184 offset:21504
	ds_read_b64_tr_b16 v[216:217], v184 offset:23552
	v_mfma_f32_32x32x16_bf16 v[48:63], v[168:171], v[224:227], v[48:63]
	ds_read_b64_tr_b16 v[224:225], v184 offset:25600
	ds_read_b64_tr_b16 v[226:227], v184 offset:27648
	v_mfma_f32_32x32x16_bf16 v[48:63], v[172:175], v[228:231], v[48:63]
	ds_read_b64_tr_b16 v[228:229], v184 offset:29696
	ds_read_b64_tr_b16 v[230:231], v184 offset:31744
	s_waitcnt lgkmcnt(0)
	v_mfma_f32_32x32x16_bf16 v[32:47], v[160:163], v[210:213], v[32:47]
	ds_read_b64_tr_b16 v[210:211], v184 offset:17920
	ds_read_b64_tr_b16 v[212:213], v184 offset:19968
	v_mfma_f32_32x32x16_bf16 v[32:47], v[164:167], v[214:217], v[32:47]
	ds_read_b64_tr_b16 v[214:215], v184 offset:22016
	ds_read_b64_tr_b16 v[216:217], v184 offset:24064
	v_mfma_f32_32x32x16_bf16 v[32:47], v[168:171], v[224:227], v[32:47]
	ds_read_b64_tr_b16 v[224:225], v184 offset:26112
	ds_read_b64_tr_b16 v[226:227], v184 offset:28160
	v_mfma_f32_32x32x16_bf16 v[32:47], v[172:175], v[228:231], v[32:47]
	ds_read_b64_tr_b16 v[228:229], v184 offset:30208
	ds_read_b64_tr_b16 v[230:231], v184 offset:32256
	s_waitcnt lgkmcnt(0)
	v_mfma_f32_32x32x16_bf16 v[16:31], v[160:163], v[210:213], v[16:31]
	v_max_f32_e32 v160, v80, v81
	v_max3_f32 v160, v160, v82, v83
	v_max3_f32 v160, v160, v84, v85
	v_max3_f32 v160, v160, v86, v87
	v_max3_f32 v160, v160, v88, v89
	v_max3_f32 v160, v160, v90, v91
	v_max3_f32 v160, v160, v92, v93
	v_mfma_f32_32x32x16_bf16 v[16:31], v[164:167], v[214:217], v[16:31]
	v_max3_f32 v160, v160, v94, v95
	v_max3_f32 v160, v160, v64, v65
	v_max3_f32 v160, v160, v66, v67
	v_max3_f32 v160, v160, v68, v69
	v_max3_f32 v160, v160, v70, v71
	v_max3_f32 v160, v160, v72, v73
	v_max3_f32 v160, v160, v74, v75
	v_max3_f32 v160, v160, v76, v77
	v_mfma_f32_32x32x16_bf16 v[16:31], v[168:171], v[224:227], v[16:31]
	v_max3_f32 v160, v160, v78, v79
	v_mov_b32_e32 v161, v160
	s_nop 1
	v_permlane32_swap_b32_e32 v160, v161
	v_max_f32_e32 v160, v160, v161
	v_sub_f32_e32 v161, v160, v206
	v_cmp_ge_f32_e32 vcc, s9, v161
	v_mfma_f32_32x32x16_bf16 v[16:31], v[172:175], v[228:231], v[16:31]
	s_cmp_eq_u64 vcc, exec
	s_cbranch_scc0 .Lattn_slow_b
	v_mov_b32_e32 v164, v206
	v_mov_b32_e32 v160, 1.0
	s_waitcnt vmcnt(4)
	ds_write_b128 v187, v[144:147] offset:16384
	ds_write_b128 v187, v[156:159] offset:24576
	ds_write_b128 v185, v[148:151] offset:49152
	ds_write_b128 v185, v[152:155] offset:57344
